# v30 + sw_layers row-0 shift loads issued before the wait for the weight rows
# speedup vs baseline: 1.0003x; 1.0003x over previous
; __device__ __forceinline__ void sw_layers(const Args& a, int l_lo, int l_hi, int wb, int nwb) {
;     ...
;         for (int u = 0; u < 2; ++u) {
;             float acc[5] = {0.f, 0.f, 0.f, 0.f, 0.f};
; #pragma unroll
;             for (int hseg = 0; hseg < 2; ++hseg) {
;                 const int k0 = hseg * 512 + 8 * lane;
;                 float wf[8]; unpack8(wv[u][hseg], wf);
; #pragma unroll
;                 for (int bb = 0; bb < 5; ++bb) {
;                     const f32x4 s0 = *(const f32x4*)(shp[u] + (size_t)bb * NMODC + k0), s1 = *(const f32x4*)(shp[u] + (size_t)bb * NMODC + k0 + 4);
;                     acc[bb] += s0[0] * wf[0] + s0[1] * wf[1] + s0[2] * wf[2] + s0[3] * wf[3] + s1[0] * wf[4] + s1[1] * wf[5] + s1[2] * wf[6] + s1[3] * wf[7];
;                 }
;             }
.LBB0_94:
	s_or_b64 exec, exec, s[40:41]
	v_readlane_b32 s8, v251, 0
	v_mul_hi_i32_i24_e32 v29, 0x1e000, v30
	v_mul_i32_i24_e32 v28, 0x1e000, v30
	v_readlane_b32 s22, v251, 14
	v_readlane_b32 s23, v251, 15
	v_mov_b32_e32 v23, 0x3000
	v_cndmask_b32_e64 v206, v23, 0, s[0:1]
	v_lshl_add_u64 v[28:29], s[22:23], 0, v[28:29]
	v_lshl_add_u64 v[28:29], v[28:29], 0, v[206:207]
	v_lshlrev_b32_e32 v206, 2, v18
	v_lshl_add_u64 v[176:177], v[28:29], 0, v[206:207]
	s_mov_b64 s[98:99], 0x6000
	v_lshl_add_u64 v[88:89], v[176:177], 0, s[98:99]
	s_mov_b64 s[98:99], 0xc000
	v_lshl_add_u64 v[90:91], v[176:177], 0, s[98:99]
	s_mov_b64 s[98:99], 0x12000
	v_lshl_add_u64 v[92:93], v[176:177], 0, s[98:99]
	s_mov_b64 s[98:99], 0x18000
	v_lshl_add_u64 v[94:95], v[176:177], 0, s[98:99]
	global_load_dwordx4 v[96:99], v[176:177], off
	global_load_dwordx4 v[100:103], v[176:177], off offset:16
	global_load_dwordx4 v[104:107], v[176:177], off offset:2048
	global_load_dwordx4 v[108:111], v[176:177], off offset:2064
	global_load_dwordx4 v[112:115], v[88:89], off
	global_load_dwordx4 v[116:119], v[88:89], off offset:16
	global_load_dwordx4 v[120:123], v[88:89], off offset:2048
	global_load_dwordx4 v[124:127], v[88:89], off offset:2064
	global_load_dwordx4 v[128:131], v[90:91], off
	global_load_dwordx4 v[132:135], v[90:91], off offset:16
	global_load_dwordx4 v[136:139], v[90:91], off offset:2048
	global_load_dwordx4 v[140:143], v[90:91], off offset:2064
	global_load_dwordx4 v[144:147], v[92:93], off
	global_load_dwordx4 v[148:151], v[92:93], off offset:16
	global_load_dwordx4 v[152:155], v[92:93], off offset:2048
	global_load_dwordx4 v[156:159], v[92:93], off offset:2064
	global_load_dwordx4 v[160:163], v[94:95], off
	global_load_dwordx4 v[164:167], v[94:95], off offset:16
	global_load_dwordx4 v[168:171], v[94:95], off offset:2048
	global_load_dwordx4 v[172:175], v[94:95], off offset:2064
	s_waitcnt vmcnt(0)
	v_lshlrev_b32_e32 v23, 16, v14
	v_and_b32_e32 v45, 0xffff0000, v14
	v_lshlrev_b32_e32 v54, 16, v15
	v_and_b32_e32 v55, 0xffff0000, v15
	v_lshl_add_u64 v[14:15], v[28:29], 0, v[206:207]
	s_nop 0
	s_nop 0
	v_lshlrev_b32_e32 v56, 16, v16
	v_and_b32_e32 v57, 0xffff0000, v16
	v_lshlrev_b32_e32 v58, 16, v17
	v_and_b32_e32 v59, 0xffff0000, v17
	s_mov_b64 s[0:1], 0x6000
	s_waitcnt vmcnt(4)
	v_and_b32_e32 v64, 0xffff0000, v13
	s_mov_b64 s[40:41], -1
	v_readlane_b32 s9, v251, 1
	v_readlane_b32 s10, v251, 2
	v_readlane_b32 s11, v251, 3
	v_readlane_b32 s12, v251, 4
	v_readlane_b32 s13, v251, 5
	v_readlane_b32 s14, v251, 6
	v_readlane_b32 s15, v251, 7
	v_readlane_b32 s16, v251, 8
	v_readlane_b32 s17, v251, 9
	v_readlane_b32 s18, v251, 10
	v_readlane_b32 s19, v251, 11
	v_readlane_b32 s20, v251, 12
	v_readlane_b32 s21, v251, 13
	s_waitcnt vmcnt(0)
	v_mul_f32_e32 v16, v97, v45
	v_fmac_f32_e32 v16, v96, v23
	v_fmac_f32_e32 v16, v98, v54
	v_fmac_f32_e32 v16, v99, v55
	v_fmac_f32_e32 v16, v100, v56
	v_fmac_f32_e32 v16, v101, v57
	v_fmac_f32_e32 v16, v102, v58
	v_fmac_f32_e32 v16, v103, v59
	v_add_f32_e32 v60, 0, v16
	v_lshl_add_u64 v[16:17], v[14:15], 0, s[0:1]
	v_add_co_u32_e64 v30, s[0:1], s7, v14
	s_nop 1
	v_addc_co_u32_e64 v31, s[0:1], 0, v15, s[0:1]
	s_nop 0
	s_nop 0
	s_mov_b64 s[0:1], 0xc000
	v_lshl_add_u64 v[28:29], v[14:15], 0, s[0:1]
	s_mov_b32 s0, 0xc000
	s_waitcnt vmcnt(1)
	v_mul_f32_e32 v16, v113, v45
	v_fmac_f32_e32 v16, v112, v23
	v_fmac_f32_e32 v16, v114, v54
	v_fmac_f32_e32 v16, v115, v55
	s_waitcnt vmcnt(0)
	v_fmac_f32_e32 v16, v116, v56
	v_fmac_f32_e32 v16, v117, v57
	v_fmac_f32_e32 v16, v118, v58
	v_fmac_f32_e32 v16, v119, v59
	v_add_f32_e32 v61, 0, v16
	v_add_co_u32_e64 v16, s[0:1], s0, v14
	s_nop 1
	v_addc_co_u32_e64 v17, s[0:1], 0, v15, s[0:1]
	s_nop 0
	s_nop 0
	s_mov_b64 s[0:1], 0x12000
	v_lshl_add_u64 v[32:33], v[14:15], 0, s[0:1]
	s_mov_b32 s0, 0x12000
	s_waitcnt vmcnt(1)
	v_mul_f32_e32 v28, v129, v45
	v_fmac_f32_e32 v28, v128, v23
	v_fmac_f32_e32 v28, v130, v54
	v_fmac_f32_e32 v28, v131, v55
	s_waitcnt vmcnt(0)
	v_fmac_f32_e32 v28, v132, v56
	v_fmac_f32_e32 v28, v133, v57
	v_fmac_f32_e32 v28, v134, v58
	v_fmac_f32_e32 v28, v135, v59
	v_add_f32_e32 v62, 0, v28
	v_add_co_u32_e64 v28, s[0:1], s0, v14
	s_nop 1
	v_addc_co_u32_e64 v29, s[0:1], 0, v15, s[0:1]
	s_nop 0
	s_nop 0
	s_mov_b64 s[0:1], 0x18000
	s_waitcnt vmcnt(1)
	v_mul_f32_e32 v32, v145, v45
	v_fmac_f32_e32 v32, v144, v23
	v_fmac_f32_e32 v32, v146, v54
	v_fmac_f32_e32 v32, v147, v55
	s_waitcnt vmcnt(0)
	v_fmac_f32_e32 v32, v148, v56
	v_fmac_f32_e32 v32, v149, v57
	v_fmac_f32_e32 v32, v150, v58
	v_fmac_f32_e32 v32, v151, v59
	v_lshl_add_u64 v[50:51], v[14:15], 0, s[0:1]
	s_mov_b32 s0, 0x18000
	v_add_f32_e32 v63, 0, v32
	v_add_co_u32_e64 v32, s[0:1], s0, v14
	s_nop 1
	v_addc_co_u32_e64 v33, s[0:1], 0, v15, s[0:1]
	s_nop 0
	s_nop 0
	s_nop 0
	s_mov_b64 s[0:1], 0x6800
	s_waitcnt vmcnt(1)
	v_mul_f32_e32 v45, v161, v45
	v_fmac_f32_e32 v45, v160, v23
	v_fmac_f32_e32 v45, v162, v54
	v_fmac_f32_e32 v45, v163, v55
	s_waitcnt vmcnt(0)
; __device__ __forceinline__ void sw_layers(const Args& a, int l_lo, int l_hi, int wb, int nwb) {
;     ...
;             for (int hseg = 0; hseg < 2; ++hseg) {
;                 const int k0 = hseg * 512 + 8 * lane;
;                 float wf[8]; unpack8(wv[u][hseg], wf);
; #pragma unroll
;                 for (int bb = 0; bb < 5; ++bb) {
;                     const f32x4 s0 = *(const f32x4*)(shp[u] + (size_t)bb * NMODC + k0), s1 = *(const f32x4*)(shp[u] + (size_t)bb * NMODC + k0 + 4);
;                     acc[bb] += s0[0] * wf[0] + s0[1] * wf[1] + s0[2] * wf[2] + s0[3] * wf[3] + s1[0] * wf[4] + s1[1] * wf[5] + s1[2] * wf[6] + s1[3] * wf[7];
;                 }
;             }
; #pragma unroll
;             for (int bb = 0; bb < 5; ++bb) acc[bb] = wave_sum(acc[bb]);
;             if (lane == 0 && okp[u]) {
; #pragma unroll
;                 for (int bb = 0; bb < 5; ++bb) dstp[u][(size_t)bb * ldp[u]] = acc[bb];
;             }
	v_fmac_f32_e32 v45, v164, v56
	v_fmac_f32_e32 v45, v165, v57
	v_fmac_f32_e32 v45, v166, v58
	v_fmac_f32_e32 v45, v167, v59
	v_add_f32_e32 v23, 0, v45
	v_lshlrev_b32_e32 v45, 16, v10
	v_and_b32_e32 v54, 0xffff0000, v10
	v_lshlrev_b32_e32 v55, 16, v11
	v_and_b32_e32 v56, 0xffff0000, v11
	v_lshlrev_b32_e32 v57, 16, v12
	v_and_b32_e32 v58, 0xffff0000, v12
	v_lshlrev_b32_e32 v59, 16, v13
	s_nop 0
	s_nop 0
	s_waitcnt vmcnt(0)
	v_mul_f32_e32 v47, v105, v54
	v_fmac_f32_e32 v47, v104, v45
	v_fmac_f32_e32 v47, v106, v55
	v_fmac_f32_e32 v47, v107, v56
	v_fmac_f32_e32 v47, v108, v57
	v_fmac_f32_e32 v47, v109, v58
	v_fmac_f32_e32 v47, v110, v59
	v_fmac_f32_e32 v47, v111, v64
	v_add_f32_e32 v10, v60, v47
	v_lshl_add_u64 v[12:13], v[14:15], 0, s[0:1]
	s_nop 0
	s_nop 0
	s_mov_b64 s[0:1], 0xc800
	v_lshl_add_u64 v[30:31], v[14:15], 0, s[0:1]
	s_mov_b64 s[0:1], 0x12800
	s_waitcnt vmcnt(1)
	v_mul_f32_e32 v11, v121, v54
	v_fmac_f32_e32 v11, v120, v45
	v_fmac_f32_e32 v11, v122, v55
	v_fmac_f32_e32 v11, v123, v56
	s_waitcnt vmcnt(0)
	v_fmac_f32_e32 v11, v124, v57
	v_fmac_f32_e32 v11, v125, v58
	v_fmac_f32_e32 v11, v126, v59
	v_fmac_f32_e32 v11, v127, v64
	s_nop 0
	s_nop 0
	v_add_f32_e32 v12, v61, v11
	v_lshl_add_u64 v[16:17], v[14:15], 0, s[0:1]
	s_mov_b64 s[0:1], 0x18800
	s_waitcnt vmcnt(1)
	v_mul_f32_e32 v11, v137, v54
	v_fmac_f32_e32 v11, v136, v45
	v_fmac_f32_e32 v11, v138, v55
	v_fmac_f32_e32 v11, v139, v56
	s_nop 0
	s_nop 0
	s_nop 0
	s_waitcnt vmcnt(2)
	v_fmac_f32_e32 v11, v140, v57
	v_fmac_f32_e32 v11, v141, v58
	v_fmac_f32_e32 v11, v142, v59
	v_fmac_f32_e32 v11, v143, v64
	v_add_f32_e32 v11, v62, v11
	s_waitcnt vmcnt(1)
	v_mul_f32_e32 v13, v153, v54
	v_fmac_f32_e32 v13, v152, v45
	v_fmac_f32_e32 v13, v154, v55
	v_lshl_add_u64 v[28:29], v[14:15], 0, s[0:1]
	v_fmac_f32_e32 v13, v155, v56
	s_nop 0
	s_nop 0
	s_nop 0
	s_waitcnt vmcnt(2)
	v_fmac_f32_e32 v13, v156, v57
	v_fmac_f32_e32 v13, v157, v58
	v_fmac_f32_e32 v13, v158, v59
	v_fmac_f32_e32 v13, v159, v64
	v_add_f32_e32 v13, v63, v13
	s_waitcnt vmcnt(1)
	v_mul_f32_e32 v15, v169, v54
	v_fmac_f32_e32 v15, v168, v45
	v_fmac_f32_e32 v15, v170, v55
	v_fmac_f32_e32 v15, v171, v56
	s_waitcnt vmcnt(0)
	v_fmac_f32_e32 v15, v172, v57
	v_fmac_f32_e32 v15, v173, v58
	v_fmac_f32_e32 v15, v174, v59
	v_fmac_f32_e32 v15, v175, v64
	v_add_f32_e32 v14, v23, v15
	ds_bpermute_b32 v15, v39, v10
	ds_bpermute_b32 v16, v39, v12
	ds_bpermute_b32 v17, v39, v11
	ds_bpermute_b32 v23, v39, v13
	ds_bpermute_b32 v28, v39, v14
	s_waitcnt lgkmcnt(4)
	v_add_f32_e32 v10, v10, v15
	s_waitcnt lgkmcnt(3)
	v_add_f32_e32 v12, v12, v16
	s_waitcnt lgkmcnt(2)
	v_add_f32_e32 v11, v11, v17
	s_waitcnt lgkmcnt(1)
	v_add_f32_e32 v13, v13, v23
	s_waitcnt lgkmcnt(0)
	v_add_f32_e32 v14, v14, v28
	ds_bpermute_b32 v15, v40, v10
	ds_bpermute_b32 v16, v40, v12
	ds_bpermute_b32 v17, v40, v11
	ds_bpermute_b32 v23, v40, v13
	ds_bpermute_b32 v28, v40, v14
	s_waitcnt lgkmcnt(4)
	v_add_f32_e32 v10, v10, v15
	s_waitcnt lgkmcnt(3)
	v_add_f32_e32 v12, v12, v16
	s_waitcnt lgkmcnt(2)
	v_add_f32_e32 v11, v11, v17
	s_waitcnt lgkmcnt(1)
	v_add_f32_e32 v13, v13, v23
	s_waitcnt lgkmcnt(0)
	v_add_f32_e32 v14, v14, v28
	ds_bpermute_b32 v15, v41, v10
	ds_bpermute_b32 v16, v41, v12
	ds_bpermute_b32 v17, v41, v11
	ds_bpermute_b32 v23, v41, v13
	ds_bpermute_b32 v28, v41, v14
	s_waitcnt lgkmcnt(4)
	v_add_f32_e32 v10, v10, v15
	s_waitcnt lgkmcnt(3)
	v_add_f32_e32 v12, v12, v16
	s_waitcnt lgkmcnt(2)
	v_add_f32_e32 v11, v11, v17
	s_waitcnt lgkmcnt(1)
	v_add_f32_e32 v13, v13, v23
	s_waitcnt lgkmcnt(0)
	v_add_f32_e32 v14, v14, v28
	ds_bpermute_b32 v15, v42, v10
	ds_bpermute_b32 v16, v42, v12
	ds_bpermute_b32 v17, v42, v11
	ds_bpermute_b32 v23, v42, v13
	ds_bpermute_b32 v28, v42, v14
	s_waitcnt lgkmcnt(4)
	v_add_f32_e32 v10, v10, v15
	s_waitcnt lgkmcnt(3)
	v_add_f32_e32 v12, v12, v16
	s_waitcnt lgkmcnt(2)
	v_add_f32_e32 v11, v11, v17
	s_waitcnt lgkmcnt(1)
	v_add_f32_e32 v13, v13, v23
	s_waitcnt lgkmcnt(0)
	v_add_f32_e32 v14, v14, v28
	ds_bpermute_b32 v15, v43, v10
	ds_bpermute_b32 v16, v43, v12
	ds_bpermute_b32 v17, v43, v11
	ds_bpermute_b32 v23, v43, v13
	ds_bpermute_b32 v28, v43, v14
	s_waitcnt lgkmcnt(4)
	v_add_f32_e32 v10, v10, v15
	s_waitcnt lgkmcnt(3)
	v_add_f32_e32 v12, v12, v16
	s_waitcnt lgkmcnt(2)
	v_add_f32_e32 v11, v11, v17
	s_waitcnt lgkmcnt(1)
	v_add_f32_e32 v13, v13, v23
	s_waitcnt lgkmcnt(0)
	v_add_f32_e32 v14, v14, v28
	ds_bpermute_b32 v15, v44, v10
	ds_bpermute_b32 v16, v44, v12
	ds_bpermute_b32 v17, v44, v11
	ds_bpermute_b32 v23, v44, v13
	ds_bpermute_b32 v28, v44, v14
	s_and_saveexec_b64 s[0:1], vcc
	s_cbranch_execz .LBB0_96
	s_waitcnt lgkmcnt(4)
	v_add_f32_e32 v10, v10, v15
	s_waitcnt lgkmcnt(2)
	v_add_f32_e32 v17, v11, v17
	global_store_dword v[24:25], v10, off
	v_lshlrev_b32_e32 v10, 2, v26
	v_mov_b32_e32 v11, v207
	s_waitcnt lgkmcnt(1)
	v_add_f32_e32 v23, v13, v23
	v_add_f32_e32 v16, v12, v16
	v_lshl_add_u64 v[12:13], v[24:25], 0, v[10:11]
	global_store_dword v[12:13], v16, off
	v_lshl_add_u64 v[12:13], v[12:13], 0, v[10:11]
	global_store_dword v[12:13], v17, off
	v_lshl_add_u64 v[12:13], v[12:13], 0, v[10:11]
	s_waitcnt lgkmcnt(0)
	v_add_f32_e32 v14, v14, v28
	v_lshl_add_u64 v[10:11], v[12:13], 0, v[10:11]
	s_orn2_b64 s[40:41], s[38:39], exec
	global_store_dword v[12:13], v23, off
	global_store_dword v[10:11], v14, off
